# P0->P1 seam: one-shot two-level barrier; start-of-kernel zeroing written through; every workgroup checks (loads hoisted before the transposes) that its barrier lines read 0 before it counts
# speedup vs baseline: 1.0043x; 1.0043x over previous
; #define LAS __attribute__((address_space(3)))
; __device__ __forceinline__ void p0_prologue(const Args& a, LAS unsigned char* lds, int vcu, int G, int tid, int lane, int wave) {
;     ...
;     LAS float* wf = (LAS float*)(lds + 73728);
;     for (int k = tid; k < 1024; k += 512) { const f32x4 w0 = *(const f32x4*)(w_in + (size_t)k * NIN + 7168), w1 = *(const f32x4*)(w_in + (size_t)k * NIN + 7172);
;         wf[0 * 1024 + k] = w0.x; wf[1 * 1024 + k] = w0.y; wf[2 * 1024 + k] = w0.z; wf[3 * 1024 + k] = w0.w; wf[4 * 1024 + k] = w1.x; wf[5 * 1024 + k] = w1.y; wf[6 * 1024 + k] = w1.z; wf[7 * 1024 + k] = w1.w; }
;     LAS float* scr = (LAS float*)(lds + wave * 8448);
;     constexpr int I1 = 16 * (NP1 / 32), IG = 16 * (NG / 32), IS = 16 * 32;
;     constexpr int NITEMS = I1 + IG + 3 * IS;
;     for (int it = gw; it < NITEMS; it += NGW) {
.LBB0_12:
	s_or_b64 exec, exec, s[0:1]
	v_cmp_eq_u32_e32 vcc, 0, v9
	s_and_saveexec_b64 s[4:5], vcc
	s_add_u32 s8, s28, 0x84000
	s_addc_u32 s9, s29, 0
	s_and_b32 s10, s2, 7
	s_lshl_b32 s10, s10, 8
	s_add_u32 s10, s8, s10
	s_addc_u32 s11, s9, 0
	v_mov_b32_e32 v88, 0
	global_load_dword v84, v88, s[10:11] offset:64 sc1
	global_load_dword v85, v88, s[10:11] offset:160 sc1
	global_load_dword v86, v88, s[8:9] offset:2112 sc1
	global_load_dword v87, v88, s[8:9] offset:2208 sc1
	s_or_b64 exec, exec, s[4:5]
	s_lshl_b32 s0, s86, 3
	v_and_b32_e32 v188, 63, v9
	s_add_i32 s62, s0, s88
	s_lshl_b32 s34, s3, 3
	s_cmpk_gt_i32 s62, 0x17ff
	v_lshlrev_b32_e32 v34, 3, v188
	s_cbranch_scc1 .LBB0_41
	v_lshlrev_b32_e32 v1, 2, v9
	v_and_b32_e32 v4, 0x7c, v1
	v_mov_b32_e32 v5, 0
	v_and_b32_e32 v1, 56, v34
	v_lshlrev_b32_e32 v10, 1, v1
	v_mov_b32_e32 v11, v5
	v_lshl_add_u64 v[26:27], s[28:29], 0, v[10:11]
	s_mov_b64 s[4:5], 0x1a00000
	v_lshl_add_u64 v[10:11], v[26:27], 0, s[4:5]
	s_mov_b64 s[4:5], 0x1600800
	v_lshl_add_u64 v[14:15], v[26:27], 0, s[4:5]
	s_mov_b64 s[4:5], 0x1600000
	v_lshl_add_u64 v[18:19], v[26:27], 0, s[4:5]
	v_lshl_add_u64 v[20:21], s[40:41], 0, v[4:5]
	s_mov_b64 s[4:5], 0x7020
	s_mul_i32 s0, s88, 0x2100
	v_lshrrev_b32_e32 v31, 3, v188
	v_lshl_add_u64 v[22:23], v[20:21], 0, s[4:5]
	s_mov_b64 s[4:5], 0x1200000
	s_add_i32 s0, s0, 0
	v_lshrrev_b32_e32 v2, 5, v188
	v_mul_u32_u24_e32 v3, 0x84, v1
	v_lshlrev_b32_e32 v1, 2, v31
	v_lshl_add_u64 v[24:25], v[26:27], 0, s[4:5]
	s_mov_b64 s[4:5], 0x400000
	s_mov_b32 s1, 0
	v_lshl_add_u64 v[6:7], s[58:59], 0, v[4:5]
	v_add_u32_e32 v8, s0, v4
	s_movk_i32 s8, 0x84
	v_add3_u32 v32, s0, v3, v1
	v_or_b32_e32 v33, 8, v31
	v_or_b32_e32 v35, 16, v31
	v_or_b32_e32 v36, 24, v31
	v_lshl_add_u64 v[12:13], s[56:57], 0, v[4:5]
	v_lshl_add_u64 v[16:17], s[54:55], 0, v[4:5]
	v_lshl_add_u64 v[26:27], v[26:27], 0, s[4:5]
	v_mov_b32_e32 v1, v2
	s_mov_b32 s9, 0x9020
	s_mov_b32 s10, s62
	s_branch .LBB0_15

; __device__ __forceinline__ unsigned f2bf(float f) { unsigned u = __builtin_bit_cast(unsigned, f); return (u + 0x7fffu + ((u >> 16) & 1u)) >> 16; }
; __device__ __forceinline__ void p0_prologue(const Args& a, LAS unsigned char* lds, int vcu, int G, int tid, int lane, int wave) {
;     ...
;     for (int i = gt; i < 8 * 128 * 128; i += NGT) { const int s = i & 127, t = (i >> 7) & 127; const float v = ((t >> 6) >= (s >> 6)) ? w_sp[i] : 0.f; WSM[i] = (bf16)f2bf(v); }
;     for (int i = gt; i < T; i += NGT) ssq[i] = 0.f;
;     __syncthreads();
.LBB0_41:
	v_cmp_eq_u32_e32 vcc, 0, v9
	s_and_saveexec_b64 s[4:5], vcc
	s_cbranch_execz .Lgz_skip
	v_or3_b32 v1, v84, v85, v86
	v_or_b32_e32 v1, v1, v87
	s_nop 0
	v_readfirstlane_b32 s12, v1
	s_cmp_eq_u32 s12, 0
	s_cbranch_scc1 .Lgz_skip
	s_add_u32 s8, s28, 0x84000
	s_addc_u32 s9, s29, 0
	s_and_b32 s10, s2, 7
	s_lshl_b32 s10, s10, 8
	s_add_u32 s10, s8, s10
	s_addc_u32 s11, s9, 0
	v_mov_b32_e32 v1, 0
	s_mov_b32 s13, 0
.Lgz_spin:
	global_load_dword v2, v1, s[10:11] offset:64 sc1
	global_load_dword v3, v1, s[10:11] offset:160 sc1
	global_load_dword v4, v1, s[8:9] offset:2112 sc1
	global_load_dword v5, v1, s[8:9] offset:2208 sc1
	s_waitcnt vmcnt(0)
	v_or3_b32 v2, v2, v3, v4
	v_or_b32_e32 v2, v2, v5
	s_nop 0
	v_readfirstlane_b32 s12, v2
	s_cmp_eq_u32 s12, 0
	s_cbranch_scc1 .Lgz_skip
	s_sleep 1
	s_add_u32 s13, s13, 1
	s_cmp_lt_u32 s13, 0x4000
	s_cbranch_scc1 .Lgz_spin
.Lgz_skip:
	s_or_b64 exec, exec, s[4:5]
	v_lshl_add_u32 v2, s86, 9, v9
	s_mov_b32 s0, 0x20000
	s_lshl_b32 s4, s3, 9
	v_cmp_gt_i32_e32 vcc, s0, v2
	s_and_saveexec_b64 s[0:1], vcc
	s_cbranch_execz .LBB0_46
	v_ashrrev_i32_e32 v3, 31, v2
	v_mov_b32_e32 v4, s46
	v_mov_b32_e32 v5, s47
	s_ashr_i32 s5, s4, 31
	v_lshl_add_u64 v[6:7], v[2:3], 1, s[28:29]
	s_mov_b64 s[8:9], 0x300000
	v_lshl_add_u64 v[4:5], v[2:3], 2, v[4:5]
	s_lshl_b64 s[6:7], s[4:5], 2
	v_lshl_add_u64 v[6:7], v[6:7], 0, s[8:9]
	s_lshl_b64 s[8:9], s[4:5], 1
	s_mov_b64 s[10:11], 0
	s_movk_i32 s5, 0x7fff
	s_mov_b32 s14, 0x1ffff
	v_mov_b32_e32 v1, v2
	s_branch .LBB0_44

; #define LAS __attribute__((address_space(3)))
; #define PH_IDS() int tid = threadIdx.x; asm volatile("" : "+v"(tid)); const int lane = tid & 63
; #define SEAM(k) do { if (IN(k) && IN((k) + 1)) { if ((k) == 0) cg::this_grid().sync(); else xcd_barrier(xbar); } } while (0)
; __global__ void __launch_bounds__(NWAVES * 64, 2) fwd_mega(Args args) {
;     ...
;     { volatile LAS unsigned* m_ = (volatile LAS unsigned*)(lds + MISC_OFF); if (threadIdx.x < 16) m_[threadIdx.x] = 0u; }
;     __syncthreads();
;     if (lo == 0) { unsigned* bz = (unsigned*)(ws + WS_BAR); for (int i = blockIdx.x * (NWAVES * 64) + threadIdx.x; i < BAR_BYTES / 4; i += gridDim.x * (NWAVES * 64)) bz[i] = 0u; }
;     XcdBarrier xbar; xbar.bar = (unsigned*)(ws + WS_BAR); xbar.x = 0; xbar.st = (volatile LAS unsigned*)(lds + MISC_OFF);
;     bf16* XN = (bf16*)args.out;
;     bf16* AO = (bf16*)(ws + WS_AO); bf16* VA = (bf16*)(ws + WS_VA); bf16* ZA = (bf16*)(ws + WS_ZA); bf16* KB = (bf16*)(ws + WS_K); bf16* VB = (bf16*)(ws + WS_V); bf16* ZB = (bf16*)(ws + WS_ZB);
;     bf16* GA = VA; bf16* GB = ZA; bf16* MG = KB;
;     float* ssq = (float*)(ws + WS_SSQ); float* logf_ = (float*)(ws + WS_LOGF); float* cc = (float*)(ws + WS_CC);
;     if (IN(0)) { PH_IDS(); p0_prologue(args, lds, vcu, G, tid, lane, wave); __syncthreads(); }
;     SEAM(0);
.LBB0_62:
	s_cmp_gt_i32 s31, 1
	s_cselect_b64 s[4:5], -1, 0
	s_and_b64 s[0:1], s[22:23], s[4:5]
	s_andn2_b64 vcc, exec, s[0:1]
	v_cmp_eq_u32_e64 s[0:1], 0, v0
	s_cbranch_vccnz .LBB0_74
	s_barrier
	s_and_saveexec_b64 s[6:7], s[0:1]
	s_cbranch_execz .LBB0_73
	buffer_wbl2 sc1
	s_waitcnt vmcnt(0)
	s_add_u32 s8, s28, 0x84000
	s_addc_u32 s9, s29, 0
	s_and_b32 s10, s2, 7
	s_lshl_b32 s10, s10, 8
	s_add_u32 s10, s8, s10
	s_addc_u32 s11, s9, 0
	v_mov_b32_e32 v1, 0
	v_mov_b32_e32 v2, 1
	global_atomic_add v3, v1, v2, s[10:11] offset:32 sc0
	s_waitcnt vmcnt(0)
	v_readfirstlane_b32 s12, v3
	s_cmp_lg_u32 s12, 31
	s_cbranch_scc1 .Lgs_member
	global_atomic_add v3, v1, v2, s[8:9] offset:2080 sc0
	s_waitcnt vmcnt(0)
	v_readfirstlane_b32 s12, v3
	s_cmp_lg_u32 s12, 7
	s_cbranch_scc1 .Lgs_leader_wait
	global_atomic_add v1, v2, s[8:9] offset:2208
	s_branch .Lgs_leader_go

; #define LAS __attribute__((address_space(3)))
; #define PH_IDS() int tid = threadIdx.x; asm volatile("" : "+v"(tid)); const int lane = tid & 63
; #define SEAM(k) do { if (IN(k) && IN((k) + 1)) { if ((k) == 0) cg::this_grid().sync(); else xcd_barrier(xbar); } } while (0)
; __global__ void __launch_bounds__(NWAVES * 64, 2) fwd_mega(Args args) {
;     ...
;     { volatile LAS unsigned* m_ = (volatile LAS unsigned*)(lds + MISC_OFF); if (threadIdx.x < 16) m_[threadIdx.x] = 0u; }
;     __syncthreads();
;     if (lo == 0) { unsigned* bz = (unsigned*)(ws + WS_BAR); for (int i = blockIdx.x * (NWAVES * 64) + threadIdx.x; i < BAR_BYTES / 4; i += gridDim.x * (NWAVES * 64)) bz[i] = 0u; }
;     XcdBarrier xbar; xbar.bar = (unsigned*)(ws + WS_BAR); xbar.x = 0; xbar.st = (volatile LAS unsigned*)(lds + MISC_OFF);
;     bf16* XN = (bf16*)args.out;
;     bf16* AO = (bf16*)(ws + WS_AO); bf16* VA = (bf16*)(ws + WS_VA); bf16* ZA = (bf16*)(ws + WS_ZA); bf16* KB = (bf16*)(ws + WS_K); bf16* VB = (bf16*)(ws + WS_V); bf16* ZB = (bf16*)(ws + WS_ZB);
;     bf16* GA = VA; bf16* GB = ZA; bf16* MG = KB;
;     float* ssq = (float*)(ws + WS_SSQ); float* logf_ = (float*)(ws + WS_LOGF); float* cc = (float*)(ws + WS_CC);
;     if (IN(0)) { PH_IDS(); p0_prologue(args, lds, vcu, G, tid, lane, wave); __syncthreads(); }
;     SEAM(0);
.Lgs_top:
	s_sleep 1
	global_load_dword v3, v1, s[8:9] offset:2208 sc1
	s_waitcnt vmcnt(0)
	v_readfirstlane_b32 s12, v3
	s_add_u32 s13, s13, 1
	s_cmp_lg_u32 s12, 0
	s_cbranch_scc1 .Lgs_top_ok
	s_cmp_lt_u32 s13, 0x4000
	s_cbranch_scc1 .Lgs_top
.Lgs_top_ok:
.Lgs_leader_go:
	global_atomic_add v1, v2, s[10:11] offset:160
	s_branch .Lgs_done

; #define LAS __attribute__((address_space(3)))
; #define PH_IDS() int tid = threadIdx.x; asm volatile("" : "+v"(tid)); const int lane = tid & 63
; #define SEAM(k) do { if (IN(k) && IN((k) + 1)) { if ((k) == 0) cg::this_grid().sync(); else xcd_barrier(xbar); } } while (0)
; __global__ void __launch_bounds__(NWAVES * 64, 2) fwd_mega(Args args) {
;     ...
;     { volatile LAS unsigned* m_ = (volatile LAS unsigned*)(lds + MISC_OFF); if (threadIdx.x < 16) m_[threadIdx.x] = 0u; }
;     __syncthreads();
;     if (lo == 0) { unsigned* bz = (unsigned*)(ws + WS_BAR); for (int i = blockIdx.x * (NWAVES * 64) + threadIdx.x; i < BAR_BYTES / 4; i += gridDim.x * (NWAVES * 64)) bz[i] = 0u; }
;     XcdBarrier xbar; xbar.bar = (unsigned*)(ws + WS_BAR); xbar.x = 0; xbar.st = (volatile LAS unsigned*)(lds + MISC_OFF);
;     bf16* XN = (bf16*)args.out;
;     bf16* AO = (bf16*)(ws + WS_AO); bf16* VA = (bf16*)(ws + WS_VA); bf16* ZA = (bf16*)(ws + WS_ZA); bf16* KB = (bf16*)(ws + WS_K); bf16* VB = (bf16*)(ws + WS_V); bf16* ZB = (bf16*)(ws + WS_ZB);
;     bf16* GA = VA; bf16* GB = ZA; bf16* MG = KB;
;     float* ssq = (float*)(ws + WS_SSQ); float* logf_ = (float*)(ws + WS_LOGF); float* cc = (float*)(ws + WS_CC);
;     if (IN(0)) { PH_IDS(); p0_prologue(args, lds, vcu, G, tid, lane, wave); __syncthreads(); }
;     SEAM(0);
.Lgs_grp:
	s_sleep 1
	global_load_dword v3, v1, s[10:11] offset:160 sc1
	s_waitcnt vmcnt(0)
	v_readfirstlane_b32 s12, v3
	s_add_u32 s13, s13, 1
	s_cmp_lg_u32 s12, 0
	s_cbranch_scc1 .Lgs_grp_ok
	s_cmp_lt_u32 s13, 0x4000
	s_cbranch_scc1 .Lgs_grp
